# pair-scoped P1->P2 barrier + P1 tile order rotated per XCD (8 different starting rounds)
# baseline (speedup 1.0000x reference)
;     __host__ __device__ bool next(int i, Unit& u) const {
;         const long L = (long)i * G + c; if (L >= nwg) return false;
;         int wgid = (int)L; { const int q = nwg / NXCD, r = nwg % NXCD, xcd = wgid % NXCD, off = wgid / NXCD; wgid = (xcd < r ? xcd * (q + 1) : r * (q + 1) + (xcd - r) * q) + off; }
;         const int nig = WGM * nN, gid = wgid / nig, fm = gid * WGM, gsz = (nM - fm) < WGM ? (nM - fm) : WGM;
;         u.pm = fm + ((wgid % nig) % gsz); u.pn = (wgid % nig) / gsz; return true;
; __global__ void __launch_bounds__(NWAVES * 64, 2) mk_fwd(Args a) {
;     ...
;             pg8::Unit u0; int pm0 = -1; if (S.next(0, u0)) pm0 = u0.pm;
.LBB0_151:
	s_ashr_i32 s2, s12, 3
	s_add_i32 s2, s17, s2
	s_ashr_i32 s3, s2, 31
	s_lshr_b32 s3, s3, 24
	s_add_i32 s3, s2, s3
	s_ashr_i32 s12, s3, 8
	s_and_b32 s3, s3, 0xff00
	s_sub_i32 s2, s2, s3
	s_sext_i32_i16 s3, s2
	s_bfe_u32 s3, s3, 0x3001c
	s_add_i32 s3, s2, s3
	s_sext_i32_i16 s16, s3
	s_and_b32 s3, s3, 0xfff8
	s_sub_i32 s2, s2, s3
	s_lshl_b32 s12, s12, 3
	s_sext_i32_i16 s2, s2
	s_add_i32 s52, s12, s2
	s_ashr_i32 s42, s16, 3
	s_cmp_lg_u32 s98, 0
	s_cbranch_scc0 .Lrot_skip0
	s_and_b32 s2, s1, 7
	s_lshl_b32 s2, s2, 2
	s_add_i32 s42, s42, s2

;     __host__ __device__ bool next(int i, Unit& u) const {
;         const long L = (long)i * G + c; if (L >= nwg) return false;
;         int wgid = (int)L; { const int q = nwg / NXCD, r = nwg % NXCD, xcd = wgid % NXCD, off = wgid / NXCD; wgid = (xcd < r ? xcd * (q + 1) : r * (q + 1) + (xcd - r) * q) + off; }
;         const int nig = WGM * nN, gid = wgid / nig, fm = gid * WGM, gsz = (nM - fm) < WGM ? (nM - fm) : WGM;
;         u.pm = fm + ((wgid % nig) % gsz); u.pn = (wgid % nig) / gsz; return true;
; template <class Epi, class Sched, bool ALIGN_EPI = false, bool SP2 = false, bool SPLITK = false>
; __device__ __forceinline__ void gemm_phase(PG8_LAS unsigned char* lds, const Gemm g, const Sched& S, const Epi& E) {
;     ...
;         const bool has_next = S.next(ui + 1, nxt);
.LBB0_158:
	s_add_i32 s68, s68, 1
	s_mul_i32 s4, s68, s79
	s_mul_hi_u32 s12, s68, s80
	s_add_i32 s12, s12, s4
	s_mul_i32 s4, s68, s80
	s_add_u32 s36, s4, s1
	s_addc_u32 s37, s12, s13
	v_mov_b64_e32 v[2:3], 0x7ff
	v_cmp_gt_i64_e32 vcc, s[36:37], v[2:3]
	v_cmp_lt_i64_e64 s[38:39], s[36:37], v[236:237]
	s_cbranch_vccnz .LBB0_164
	s_cmp_lg_u32 s98, 0
	s_cbranch_scc0 .Lrot_skip1
	s_and_b32 s4, s1, 7
	s_nop 0
	s_add_i32 s4, s4, s68
	s_and_b32 s4, s4, 7
	s_mul_i32 s4, s4, s80
	s_add_i32 s36, s4, s1
